# grid barrier: the first workgroup to arrive on each XCD issues an early buffer_wbl2 before spinning, so the last arriver's waited write-back has fewer dirty lines left; on top of v53
# baseline (speedup 1.0000x reference)
.LBB0_94:
	s_or_b64 exec, exec, s[8:9]
	v_cvt_f32_u32_e32 v4, v2
	s_waitcnt vmcnt(0)
	v_readfirstlane_b32 s6, v3
	v_sub_u32_e32 v3, 0, v2
	v_rcp_iflag_f32_e32 v4, v4
	v_add_u32_e32 v5, s6, v1
	v_mul_f32_e32 v4, 0x4f7ffffe, v4
	v_cvt_u32_f32_e32 v4, v4
	v_mul_lo_u32 v1, v3, v4
	v_mul_hi_u32 v1, v4, v1
	v_add_u32_e32 v1, v4, v1
	v_mul_hi_u32 v1, v5, v1
	v_mul_lo_u32 v3, v1, v2
	v_sub_u32_e32 v3, v5, v3
	v_add_u32_e32 v4, 1, v1
	v_cmp_ge_u32_e32 vcc, v3, v2
	s_nop 1
	v_cndmask_b32_e32 v1, v1, v4, vcc
	v_sub_u32_e32 v4, v3, v2
	v_cndmask_b32_e32 v3, v3, v4, vcc
	v_add_u32_e32 v4, 1, v1
	v_cmp_ge_u32_e32 vcc, v3, v2
	v_add_u32_e32 v3, 1, v5
	s_nop 0
	v_cndmask_b32_e32 v1, v1, v4, vcc
	v_mul_lo_u32 v4, v2, v1
	v_add_u32_e32 v2, v4, v2
	v_cmp_ne_u32_e32 vcc, v3, v2
	s_and_saveexec_b64 s[6:7], vcc
	s_xor_b64 s[6:7], exec, s[6:7]
	s_cbranch_execz .LBB0_108
	s_waitcnt lgkmcnt(0)
	v_mov_b32_e32 v0, 0x2000
	global_load_dword v0, v0, s[4:5] offset:1024 sc1
	s_add_u32 s16, s4, 0x2400
	s_addc_u32 s17, s5, 0
	s_waitcnt vmcnt(0)
	v_cmp_eq_u32_e32 vcc, v0, v1
	s_and_saveexec_b64 s[8:9], vcc
	s_cbranch_execz .LBB0_107
	v_cmp_eq_u32_e32 vcc, v5, v4
	s_cbranch_vccz .Lewb_skip0
	buffer_wbl2 sc1
.Lewb_skip0:
	s_add_u32 s14, s34, 0x321e200
	s_addc_u32 s15, s35, 0
	s_mov_b32 s26, 1
	s_mov_b64 s[18:19], 0
	v_mov_b32_e32 v0, 0
	s_branch .LBB0_98

.LBB0_285:
	s_or_b64 exec, exec, s[8:9]
	v_cvt_f32_u32_e32 v4, v2
	s_waitcnt vmcnt(0)
	v_readfirstlane_b32 s6, v3
	v_sub_u32_e32 v3, 0, v2
	v_rcp_iflag_f32_e32 v4, v4
	v_add_u32_e32 v5, s6, v1
	v_mul_f32_e32 v4, 0x4f7ffffe, v4
	v_cvt_u32_f32_e32 v4, v4
	v_mul_lo_u32 v1, v3, v4
	v_mul_hi_u32 v1, v4, v1
	v_add_u32_e32 v1, v4, v1
	v_mul_hi_u32 v1, v5, v1
	v_mul_lo_u32 v3, v1, v2
	v_sub_u32_e32 v3, v5, v3
	v_add_u32_e32 v4, 1, v1
	v_cmp_ge_u32_e32 vcc, v3, v2
	s_nop 1
	v_cndmask_b32_e32 v1, v1, v4, vcc
	v_sub_u32_e32 v4, v3, v2
	v_cndmask_b32_e32 v3, v3, v4, vcc
	v_add_u32_e32 v4, 1, v1
	v_cmp_ge_u32_e32 vcc, v3, v2
	v_add_u32_e32 v3, 1, v5
	s_nop 0
	v_cndmask_b32_e32 v1, v1, v4, vcc
	v_mul_lo_u32 v4, v2, v1
	v_add_u32_e32 v2, v4, v2
	v_cmp_ne_u32_e32 vcc, v3, v2
	s_and_saveexec_b64 s[6:7], vcc
	s_xor_b64 s[6:7], exec, s[6:7]
	s_cbranch_execz .LBB0_299
	s_waitcnt lgkmcnt(0)
	v_mov_b32_e32 v0, 0x2000
	global_load_dword v0, v0, s[4:5] offset:1024 sc1
	s_add_u32 s18, s4, 0x2400
	s_addc_u32 s19, s5, 0
	s_waitcnt vmcnt(0)
	v_cmp_eq_u32_e32 vcc, v0, v1
	s_and_saveexec_b64 s[8:9], vcc
	s_cbranch_execz .LBB0_298
	v_cmp_eq_u32_e32 vcc, v5, v4
	s_cbranch_vccz .Lewb_skip2
	buffer_wbl2 sc1
.Lewb_skip2:
	s_add_u32 s16, s34, 0x321e200
	s_addc_u32 s17, s35, 0
	s_mov_b32 s26, 1
	s_mov_b64 s[20:21], 0
	v_mov_b32_e32 v0, 0
	s_branch .LBB0_289

.LBB0_348:
	s_or_b64 exec, exec, s[16:17]
	v_cvt_f32_u32_e32 v4, v2
	s_waitcnt vmcnt(0)
	v_readfirstlane_b32 s3, v3
	v_sub_u32_e32 v3, 0, v2
	v_rcp_iflag_f32_e32 v4, v4
	v_add_u32_e32 v5, s3, v1
	v_mul_f32_e32 v4, 0x4f7ffffe, v4
	v_cvt_u32_f32_e32 v4, v4
	v_mul_lo_u32 v1, v3, v4
	v_mul_hi_u32 v1, v4, v1
	v_add_u32_e32 v1, v4, v1
	v_mul_hi_u32 v1, v5, v1
	v_mul_lo_u32 v3, v1, v2
	v_sub_u32_e32 v3, v5, v3
	v_add_u32_e32 v4, 1, v1
	v_cmp_ge_u32_e32 vcc, v3, v2
	s_nop 1
	v_cndmask_b32_e32 v1, v1, v4, vcc
	v_sub_u32_e32 v4, v3, v2
	v_cndmask_b32_e32 v3, v3, v4, vcc
	v_add_u32_e32 v4, 1, v1
	v_cmp_ge_u32_e32 vcc, v3, v2
	v_add_u32_e32 v3, 1, v5
	s_nop 0
	v_cndmask_b32_e32 v1, v1, v4, vcc
	v_mul_lo_u32 v4, v2, v1
	v_add_u32_e32 v2, v4, v2
	v_cmp_ne_u32_e32 vcc, v3, v2
	s_and_saveexec_b64 s[4:5], vcc
	s_xor_b64 s[8:9], exec, s[4:5]
	s_cbranch_execz .LBB0_362
	s_waitcnt lgkmcnt(0)
	v_mov_b32_e32 v0, 0x2000
	global_load_dword v0, v0, s[6:7] offset:1024 sc1
	s_add_u32 s20, s6, 0x2400
	s_addc_u32 s21, s7, 0
	s_waitcnt vmcnt(0)
	v_cmp_eq_u32_e32 vcc, v0, v1
	s_and_saveexec_b64 s[16:17], vcc
	s_cbranch_execz .LBB0_361
	v_cmp_eq_u32_e32 vcc, v5, v4
	s_cbranch_vccz .Lewb_skip3
	buffer_wbl2 sc1
.Lewb_skip3:
	s_add_u32 s18, s34, 0x321e200
	s_addc_u32 s19, s35, 0
	s_mov_b32 s3, 1
	s_mov_b64 s[22:23], 0
	v_mov_b32_e32 v0, 0
	s_branch .LBB0_352

.LBB0_533:
	s_or_b64 exec, exec, s[12:13]
	v_cvt_f32_u32_e32 v4, v2
	s_waitcnt vmcnt(0)
	v_readfirstlane_b32 s3, v3
	v_sub_u32_e32 v3, 0, v2
	v_rcp_iflag_f32_e32 v4, v4
	v_add_u32_e32 v5, s3, v1
	v_mul_f32_e32 v4, 0x4f7ffffe, v4
	v_cvt_u32_f32_e32 v4, v4
	v_mul_lo_u32 v1, v3, v4
	v_mul_hi_u32 v1, v4, v1
	v_add_u32_e32 v1, v4, v1
	v_mul_hi_u32 v1, v5, v1
	v_mul_lo_u32 v3, v1, v2
	v_sub_u32_e32 v3, v5, v3
	v_add_u32_e32 v4, 1, v1
	v_cmp_ge_u32_e32 vcc, v3, v2
	s_nop 1
	v_cndmask_b32_e32 v1, v1, v4, vcc
	v_sub_u32_e32 v4, v3, v2
	v_cndmask_b32_e32 v3, v3, v4, vcc
	v_add_u32_e32 v4, 1, v1
	v_cmp_ge_u32_e32 vcc, v3, v2
	v_add_u32_e32 v3, 1, v5
	s_nop 0
	v_cndmask_b32_e32 v1, v1, v4, vcc
	v_mul_lo_u32 v4, v2, v1
	v_add_u32_e32 v2, v4, v2
	v_cmp_ne_u32_e32 vcc, v3, v2
	s_and_saveexec_b64 s[4:5], vcc
	s_xor_b64 s[8:9], exec, s[4:5]
	s_cbranch_execz .LBB0_547
	s_waitcnt lgkmcnt(0)
	v_mov_b32_e32 v0, 0x2000
	global_load_dword v0, v0, s[6:7] offset:1024 sc1
	s_add_u32 s20, s6, 0x2400
	s_addc_u32 s21, s7, 0
	s_waitcnt vmcnt(0)
	v_cmp_eq_u32_e32 vcc, v0, v1
	s_and_saveexec_b64 s[12:13], vcc
	s_cbranch_execz .LBB0_546
	v_cmp_eq_u32_e32 vcc, v5, v4
	s_cbranch_vccz .Lewb_skip4
	buffer_wbl2 sc1

.LBB0_620:
	s_or_b64 exec, exec, s[10:11]
	v_cvt_f32_u32_e32 v4, v2
	s_waitcnt vmcnt(0)
	v_readfirstlane_b32 s3, v3
	v_sub_u32_e32 v3, 0, v2
	v_rcp_iflag_f32_e32 v4, v4
	v_add_u32_e32 v5, s3, v1
	v_mul_f32_e32 v4, 0x4f7ffffe, v4
	v_cvt_u32_f32_e32 v4, v4
	v_mul_lo_u32 v1, v3, v4
	v_mul_hi_u32 v1, v4, v1
	v_add_u32_e32 v1, v4, v1
	v_mul_hi_u32 v1, v5, v1
	v_mul_lo_u32 v3, v1, v2
	v_sub_u32_e32 v3, v5, v3
	v_add_u32_e32 v4, 1, v1
	v_cmp_ge_u32_e32 vcc, v3, v2
	s_nop 1
	v_cndmask_b32_e32 v1, v1, v4, vcc
	v_sub_u32_e32 v4, v3, v2
	v_cndmask_b32_e32 v3, v3, v4, vcc
	v_add_u32_e32 v4, 1, v1
	v_cmp_ge_u32_e32 vcc, v3, v2
	v_add_u32_e32 v3, 1, v5
	s_nop 0
	v_cndmask_b32_e32 v1, v1, v4, vcc
	v_mul_lo_u32 v4, v2, v1
	v_add_u32_e32 v2, v4, v2
	v_cmp_ne_u32_e32 vcc, v3, v2
	s_and_saveexec_b64 s[4:5], vcc
	s_xor_b64 s[8:9], exec, s[4:5]
	s_cbranch_execz .LBB0_634
	s_waitcnt lgkmcnt(0)
	v_mov_b32_e32 v0, 0x2000
	global_load_dword v0, v0, s[6:7] offset:1024 sc1
	s_add_u32 s16, s6, 0x2400
	s_addc_u32 s17, s7, 0
	s_waitcnt vmcnt(0)
	v_cmp_eq_u32_e32 vcc, v0, v1
	s_and_saveexec_b64 s[10:11], vcc
	s_cbranch_execz .LBB0_633
	v_cmp_eq_u32_e32 vcc, v5, v4
	s_cbranch_vccz .Lewb_skip5
	buffer_wbl2 sc1
.Lewb_skip5:
	s_add_u32 s12, s34, 0x321e200
	s_addc_u32 s13, s35, 0
	s_mov_b32 s3, 1
	s_mov_b64 s[18:19], 0
	v_mov_b32_e32 v0, 0
	s_branch .LBB0_624

.LBB0_781:
	s_or_b64 exec, exec, s[12:13]
	v_cvt_f32_u32_e32 v4, v2
	s_waitcnt vmcnt(0)
	v_readfirstlane_b32 s3, v3
	v_sub_u32_e32 v3, 0, v2
	v_rcp_iflag_f32_e32 v4, v4
	v_add_u32_e32 v5, s3, v1
	v_mul_f32_e32 v4, 0x4f7ffffe, v4
	v_cvt_u32_f32_e32 v4, v4
	v_mul_lo_u32 v1, v3, v4
	v_mul_hi_u32 v1, v4, v1
	v_add_u32_e32 v1, v4, v1
	v_mul_hi_u32 v1, v5, v1
	v_mul_lo_u32 v3, v1, v2
	v_sub_u32_e32 v3, v5, v3
	v_add_u32_e32 v4, 1, v1
	v_cmp_ge_u32_e32 vcc, v3, v2
	s_nop 1
	v_cndmask_b32_e32 v1, v1, v4, vcc
	v_sub_u32_e32 v4, v3, v2
	v_cndmask_b32_e32 v3, v3, v4, vcc
	v_add_u32_e32 v4, 1, v1
	v_cmp_ge_u32_e32 vcc, v3, v2
	v_add_u32_e32 v3, 1, v5
	s_nop 0
	v_cndmask_b32_e32 v1, v1, v4, vcc
	v_mul_lo_u32 v4, v2, v1
	v_add_u32_e32 v2, v4, v2
	v_cmp_ne_u32_e32 vcc, v3, v2
	s_and_saveexec_b64 s[4:5], vcc
	s_xor_b64 s[10:11], exec, s[4:5]
	s_cbranch_execz .LBB0_795
	s_waitcnt lgkmcnt(0)
	v_mov_b32_e32 v0, 0x2000
	global_load_dword v0, v0, s[8:9] offset:1024 sc1
	s_add_u32 s16, s8, 0x2400
	s_addc_u32 s17, s9, 0
	s_waitcnt vmcnt(0)
	v_cmp_eq_u32_e32 vcc, v0, v1
	s_and_saveexec_b64 s[12:13], vcc
	s_cbranch_execz .LBB0_794
	v_cmp_eq_u32_e32 vcc, v5, v4
	s_cbranch_vccz .Lewb_skip7
	buffer_wbl2 sc1
.Lewb_skip7:
	s_add_u32 s14, s34, 0x321e200
	s_addc_u32 s15, s35, 0
	s_mov_b32 s3, 1
	s_mov_b64 s[18:19], 0
	v_mov_b32_e32 v0, 0
	s_branch .LBB0_785

.LBB0_1174:
	s_or_b64 exec, exec, s[8:9]
	v_cvt_f32_u32_e32 v4, v2
	s_waitcnt vmcnt(0)
	v_readfirstlane_b32 s4, v3
	v_sub_u32_e32 v3, 0, v2
	v_rcp_iflag_f32_e32 v4, v4
	v_add_u32_e32 v5, s4, v1
	v_mul_f32_e32 v4, 0x4f7ffffe, v4
	v_cvt_u32_f32_e32 v4, v4
	v_mul_lo_u32 v1, v3, v4
	v_mul_hi_u32 v1, v4, v1
	v_add_u32_e32 v1, v4, v1
	v_mul_hi_u32 v1, v5, v1
	v_mul_lo_u32 v3, v1, v2
	v_sub_u32_e32 v3, v5, v3
	v_add_u32_e32 v4, 1, v1
	v_cmp_ge_u32_e32 vcc, v3, v2
	s_nop 1
	v_cndmask_b32_e32 v1, v1, v4, vcc
	v_sub_u32_e32 v4, v3, v2
	v_cndmask_b32_e32 v3, v3, v4, vcc
	v_add_u32_e32 v4, 1, v1
	v_cmp_ge_u32_e32 vcc, v3, v2
	v_add_u32_e32 v3, 1, v5
	s_nop 0
	v_cndmask_b32_e32 v1, v1, v4, vcc
	v_mul_lo_u32 v4, v2, v1
	v_add_u32_e32 v2, v4, v2
	v_cmp_ne_u32_e32 vcc, v3, v2
	s_and_saveexec_b64 s[4:5], vcc
	s_xor_b64 s[6:7], exec, s[4:5]
	s_cbranch_execz .LBB0_1188
	s_waitcnt lgkmcnt(0)
	v_mov_b32_e32 v0, 0x2000
	global_load_dword v0, v0, s[2:3] offset:1024 sc1
	s_add_u32 s12, s2, 0x2400
	s_addc_u32 s13, s3, 0
	s_waitcnt vmcnt(0)
	v_cmp_eq_u32_e32 vcc, v0, v1
	s_and_saveexec_b64 s[8:9], vcc
	s_cbranch_execz .LBB0_1187
	v_cmp_eq_u32_e32 vcc, v5, v4
	s_cbranch_vccz .Lewb_skip13
	buffer_wbl2 sc1
.Lewb_skip13:
	s_add_u32 s10, s34, 0x321e200
	s_addc_u32 s11, s35, 0
	s_mov_b32 s4, 1
	s_mov_b64 s[14:15], 0
	v_mov_b32_e32 v0, 0
	s_branch .LBB0_1178
